# P2 and P8 swiglu epilogues visit row groups in a per-wave rotated order (eight instruction streams instead of one)
# baseline (speedup 1.0000x reference)
; __device__ __forceinline__ u32x4 pack8(const f32x4 a, const f32x4 b) { u32x4 w; w.x = cvt_pk_bf16(a[0], a[1]); w.y = cvt_pk_bf16(a[2], a[3]); w.z = cvt_pk_bf16(b[0], b[1]); w.w = cvt_pk_bf16(b[2], b[3]); return w; }
; __device__ __forceinline__ float sigm(float v) { return __builtin_amdgcn_rcpf(1.f + __expf(-v)); }
; #define EPI_ROWS _Pragma("unroll") for (int ai = 0; ai < 2; ++ai) _Pragma("unroll") for (int m = 0; m < 4; ++m)
;     __device__ __forceinline__ void operator()(const f32x4 (&acc)[2][2][4][2], const Unit& u, int wr, int wc, int fr, int fq) const {
;     ...
;         EPI_ROWS { const int row = EPI_ROW;
;             f32x4 a0 = acc[ai][0][m][0], a1 = acc[ai][0][m][1], b0 = acc[ai][1][m][0], b1 = acc[ai][1][m][1];
;             if (NORM) { const float rs = rsv[ai][m]; a0 = a0 * rs + ba0; a1 = a1 * rs + ba1; b0 = b0 * rs + bb0; b1 = b1 * rs + bb1; }
;             f32x4 o0, o1;
; #pragma unroll
;             for (int i = 0; i < 4; ++i) { o0[i] = a0[i] * sigm(a0[i]) * b0[i]; o1[i] = a1[i] * sigm(a1[i]) * b1[i]; }
;             *(u32x4*)(act + (size_t)(row >> 1) * (2 * DFF) + (u.pn * 4 + wc) * 64 + (row & 1) * 32 + fq * 8) = pack8(o0, o1); }
.LBB0_211:
	v_mov_b32_e32 v154, 0xbfb8aa3b
	v_mov_b32_e32 v155, 0xbfb8aa3b
	v_lshrrev_b32_e32 v180, 1, v1
	v_mul_u32_u24_e32 v180, 0x2c00, v180
	v_and_b32_e32 v181, 1, v1
	v_lshl_add_u32 v180, v181, 6, v180
	v_lshl_add_u32 v180, v148, 4, v180
	s_lshl_b32 s13, s20, 8
	s_add_i32 s13, s13, s41
	s_lshr_b32 s13, s13, 1
	s_mul_i32 s13, s13, 0x2c00
	s_lshl_b32 s22, s21, 8
	s_or_b32 s22, s22, s45
	s_lshl_b32 s22, s22, 1
	s_add_u32 s13, s13, s22
	s_add_u32 s22, s6, s13
	s_addc_u32 s23, s7, 0
	s_lshr_b32 s98, s41, 4
	s_lshr_b32 s99, s45, 6
	s_add_u32 s98, s98, s99
	s_mov_b32 s99, 8
	s_cmp_eq_u32 s98, 1
	s_cbranch_scc1 .Lp2e_rg1
	s_cmp_eq_u32 s98, 2
	s_cbranch_scc1 .Lp2e_rg2
	s_cmp_eq_u32 s98, 3
	s_cbranch_scc1 .Lp2e_rg3
	s_cmp_eq_u32 s98, 4
	s_cbranch_scc1 .Lp2e_rg4
	s_cmp_eq_u32 s98, 5
	s_cbranch_scc1 .Lp2e_rg5
	s_cmp_eq_u32 s98, 6
	s_cbranch_scc1 .Lp2e_rg6
	s_cmp_eq_u32 s98, 7
	s_cbranch_scc1 .Lp2e_rg7
.Lp2e_rg0:
	s_add_u32 s100, s22, 0x0
	s_addc_u32 s101, s23, 0
	v_pk_mul_f32 v[156:157], v[154:155], v[126:127]
	v_pk_mul_f32 v[158:159], v[154:155], v[128:129]
	v_pk_mul_f32 v[160:161], v[154:155], v[122:123]
	v_pk_mul_f32 v[162:163], v[154:155], v[124:125]
	v_exp_f32_e32 v156, v156
	v_exp_f32_e32 v157, v157
	v_exp_f32_e32 v158, v158
	v_exp_f32_e32 v159, v159
	v_exp_f32_e32 v160, v160
	v_exp_f32_e32 v161, v161
	v_exp_f32_e32 v162, v162
	v_exp_f32_e32 v163, v163
	v_pk_add_f32 v[156:157], v[156:157], 1.0 op_sel_hi:[1,0]
	v_pk_add_f32 v[158:159], v[158:159], 1.0 op_sel_hi:[1,0]
	v_pk_add_f32 v[160:161], v[160:161], 1.0 op_sel_hi:[1,0]
	v_pk_add_f32 v[162:163], v[162:163], 1.0 op_sel_hi:[1,0]
	v_rcp_f32_e32 v156, v156
	v_rcp_f32_e32 v157, v157
	v_rcp_f32_e32 v158, v158
	v_rcp_f32_e32 v159, v159
	v_rcp_f32_e32 v160, v160
	v_rcp_f32_e32 v161, v161
	v_rcp_f32_e32 v162, v162
	v_rcp_f32_e32 v163, v163
	v_pk_mul_f32 v[156:157], v[126:127], v[156:157]
	v_pk_mul_f32 v[158:159], v[128:129], v[158:159]
	v_pk_mul_f32 v[160:161], v[122:123], v[160:161]
	v_pk_mul_f32 v[162:163], v[124:125], v[162:163]
	v_pk_mul_f32 v[156:157], v[156:157], v[118:119]
	v_pk_mul_f32 v[158:159], v[158:159], v[120:121]
	v_pk_mul_f32 v[160:161], v[160:161], v[114:115]
	v_pk_mul_f32 v[162:163], v[162:163], v[116:117]
	v_cvt_pk_bf16_f32 v172, v156, v157
	v_cvt_pk_bf16_f32 v173, v158, v159
	v_cvt_pk_bf16_f32 v174, v160, v161
	v_cvt_pk_bf16_f32 v175, v162, v163
	global_store_dwordx4 v180, v[172:175], s[100:101]
	s_add_i32 s99, s99, -1
	s_cmp_eq_u32 s99, 0
	s_cbranch_scc1 .Lp2e_done
.Lp2e_rg1:
	s_add_u32 s100, s22, 0x16000
	s_addc_u32 s101, s23, 0
	v_pk_mul_f32 v[164:165], v[154:155], v[110:111]
	v_pk_mul_f32 v[166:167], v[154:155], v[112:113]
	v_pk_mul_f32 v[168:169], v[154:155], v[106:107]
	v_pk_mul_f32 v[170:171], v[154:155], v[108:109]
	v_exp_f32_e32 v164, v164
	v_exp_f32_e32 v165, v165
	v_exp_f32_e32 v166, v166
	v_exp_f32_e32 v167, v167
	v_exp_f32_e32 v168, v168
	v_exp_f32_e32 v169, v169
	v_exp_f32_e32 v170, v170
	v_exp_f32_e32 v171, v171
	v_pk_add_f32 v[164:165], v[164:165], 1.0 op_sel_hi:[1,0]
	v_pk_add_f32 v[166:167], v[166:167], 1.0 op_sel_hi:[1,0]
	v_pk_add_f32 v[168:169], v[168:169], 1.0 op_sel_hi:[1,0]
	v_pk_add_f32 v[170:171], v[170:171], 1.0 op_sel_hi:[1,0]
	v_rcp_f32_e32 v164, v164
	v_rcp_f32_e32 v165, v165
	v_rcp_f32_e32 v166, v166
	v_rcp_f32_e32 v167, v167
	v_rcp_f32_e32 v168, v168
	v_rcp_f32_e32 v169, v169
	v_rcp_f32_e32 v170, v170
	v_rcp_f32_e32 v171, v171
	v_pk_mul_f32 v[164:165], v[110:111], v[164:165]
	v_pk_mul_f32 v[166:167], v[112:113], v[166:167]
	v_pk_mul_f32 v[168:169], v[106:107], v[168:169]
	v_pk_mul_f32 v[170:171], v[108:109], v[170:171]
	v_pk_mul_f32 v[164:165], v[164:165], v[102:103]
	v_pk_mul_f32 v[166:167], v[166:167], v[104:105]
	v_pk_mul_f32 v[168:169], v[168:169], v[98:99]
	v_pk_mul_f32 v[170:171], v[170:171], v[100:101]
	v_cvt_pk_bf16_f32 v176, v164, v165
	v_cvt_pk_bf16_f32 v177, v166, v167
	v_cvt_pk_bf16_f32 v178, v168, v169
	v_cvt_pk_bf16_f32 v179, v170, v171
	global_store_dwordx4 v180, v[176:179], s[100:101]
	s_add_i32 s99, s99, -1
	s_cmp_eq_u32 s99, 0
	s_cbranch_scc1 .Lp2e_done
.Lp2e_rg2:
	s_add_u32 s100, s22, 0x2c000
	s_addc_u32 s101, s23, 0
	v_pk_mul_f32 v[156:157], v[154:155], v[94:95]
	v_pk_mul_f32 v[158:159], v[154:155], v[96:97]
	v_pk_mul_f32 v[160:161], v[154:155], v[90:91]
	v_pk_mul_f32 v[162:163], v[154:155], v[92:93]
	v_exp_f32_e32 v156, v156
	v_exp_f32_e32 v157, v157
	v_exp_f32_e32 v158, v158
	v_exp_f32_e32 v159, v159
	v_exp_f32_e32 v160, v160
	v_exp_f32_e32 v161, v161
	v_exp_f32_e32 v162, v162
	v_exp_f32_e32 v163, v163
	v_pk_add_f32 v[156:157], v[156:157], 1.0 op_sel_hi:[1,0]
	v_pk_add_f32 v[158:159], v[158:159], 1.0 op_sel_hi:[1,0]
	v_pk_add_f32 v[160:161], v[160:161], 1.0 op_sel_hi:[1,0]
	v_pk_add_f32 v[162:163], v[162:163], 1.0 op_sel_hi:[1,0]
	v_rcp_f32_e32 v156, v156
	v_rcp_f32_e32 v157, v157
	v_rcp_f32_e32 v158, v158
	v_rcp_f32_e32 v159, v159
	v_rcp_f32_e32 v160, v160
	v_rcp_f32_e32 v161, v161
	v_rcp_f32_e32 v162, v162
	v_rcp_f32_e32 v163, v163
	v_pk_mul_f32 v[156:157], v[94:95], v[156:157]
	v_pk_mul_f32 v[158:159], v[96:97], v[158:159]
	v_pk_mul_f32 v[160:161], v[90:91], v[160:161]
	v_pk_mul_f32 v[162:163], v[92:93], v[162:163]
	v_pk_mul_f32 v[156:157], v[156:157], v[86:87]
	v_pk_mul_f32 v[158:159], v[158:159], v[88:89]
	v_pk_mul_f32 v[160:161], v[160:161], v[82:83]
	v_pk_mul_f32 v[162:163], v[162:163], v[84:85]
	v_cvt_pk_bf16_f32 v172, v156, v157
	v_cvt_pk_bf16_f32 v173, v158, v159
	v_cvt_pk_bf16_f32 v174, v160, v161
	v_cvt_pk_bf16_f32 v175, v162, v163
	global_store_dwordx4 v180, v[172:175], s[100:101]
	s_add_i32 s99, s99, -1
	s_cmp_eq_u32 s99, 0
	s_cbranch_scc1 .Lp2e_done
; __device__ __forceinline__ u32x4 pack8(const f32x4 a, const f32x4 b) { u32x4 w; w.x = cvt_pk_bf16(a[0], a[1]); w.y = cvt_pk_bf16(a[2], a[3]); w.z = cvt_pk_bf16(b[0], b[1]); w.w = cvt_pk_bf16(b[2], b[3]); return w; }
; __device__ __forceinline__ float sigm(float v) { return __builtin_amdgcn_rcpf(1.f + __expf(-v)); }
; #define EPI_ROWS _Pragma("unroll") for (int ai = 0; ai < 2; ++ai) _Pragma("unroll") for (int m = 0; m < 4; ++m)
;     __device__ __forceinline__ void operator()(const f32x4 (&acc)[2][2][4][2], const Unit& u, int wr, int wc, int fr, int fq) const {
;     ...
;         EPI_ROWS { const int row = EPI_ROW;
;             f32x4 a0 = acc[ai][0][m][0], a1 = acc[ai][0][m][1], b0 = acc[ai][1][m][0], b1 = acc[ai][1][m][1];
;             if (NORM) { const float rs = rsv[ai][m]; a0 = a0 * rs + ba0; a1 = a1 * rs + ba1; b0 = b0 * rs + bb0; b1 = b1 * rs + bb1; }
;             f32x4 o0, o1;
; #pragma unroll
;             for (int i = 0; i < 4; ++i) { o0[i] = a0[i] * sigm(a0[i]) * b0[i]; o1[i] = a1[i] * sigm(a1[i]) * b1[i]; }
;             *(u32x4*)(act + (size_t)(row >> 1) * (2 * DFF) + (u.pn * 4 + wc) * 64 + (row & 1) * 32 + fq * 8) = pack8(o0, o1); }
.Lp2e_rg3:
	s_add_u32 s100, s22, 0x42000
	s_addc_u32 s101, s23, 0
	v_pk_mul_f32 v[164:165], v[154:155], v[78:79]
	v_pk_mul_f32 v[166:167], v[154:155], v[80:81]
	v_pk_mul_f32 v[168:169], v[154:155], v[74:75]
	v_pk_mul_f32 v[170:171], v[154:155], v[76:77]
	v_exp_f32_e32 v164, v164
	v_exp_f32_e32 v165, v165
	v_exp_f32_e32 v166, v166
	v_exp_f32_e32 v167, v167
	v_exp_f32_e32 v168, v168
	v_exp_f32_e32 v169, v169
	v_exp_f32_e32 v170, v170
	v_exp_f32_e32 v171, v171
	v_pk_add_f32 v[164:165], v[164:165], 1.0 op_sel_hi:[1,0]
	v_pk_add_f32 v[166:167], v[166:167], 1.0 op_sel_hi:[1,0]
	v_pk_add_f32 v[168:169], v[168:169], 1.0 op_sel_hi:[1,0]
	v_pk_add_f32 v[170:171], v[170:171], 1.0 op_sel_hi:[1,0]
	v_rcp_f32_e32 v164, v164
	v_rcp_f32_e32 v165, v165
	v_rcp_f32_e32 v166, v166
	v_rcp_f32_e32 v167, v167
	v_rcp_f32_e32 v168, v168
	v_rcp_f32_e32 v169, v169
	v_rcp_f32_e32 v170, v170
	v_rcp_f32_e32 v171, v171
	v_pk_mul_f32 v[164:165], v[78:79], v[164:165]
	v_pk_mul_f32 v[166:167], v[80:81], v[166:167]
	v_pk_mul_f32 v[168:169], v[74:75], v[168:169]
	v_pk_mul_f32 v[170:171], v[76:77], v[170:171]
	v_pk_mul_f32 v[164:165], v[164:165], v[70:71]
	v_pk_mul_f32 v[166:167], v[166:167], v[72:73]
	v_pk_mul_f32 v[168:169], v[168:169], v[66:67]
	v_pk_mul_f32 v[170:171], v[170:171], v[68:69]
	v_cvt_pk_bf16_f32 v176, v164, v165
	v_cvt_pk_bf16_f32 v177, v166, v167
	v_cvt_pk_bf16_f32 v178, v168, v169
	v_cvt_pk_bf16_f32 v179, v170, v171
	global_store_dwordx4 v180, v[176:179], s[100:101]
	s_add_i32 s99, s99, -1
	s_cmp_eq_u32 s99, 0
	s_cbranch_scc1 .Lp2e_done
.Lp2e_rg4:
	s_add_u32 s100, s22, 0xb0000
	s_addc_u32 s101, s23, 0
	v_pk_mul_f32 v[156:157], v[154:155], v[62:63]
	v_pk_mul_f32 v[158:159], v[154:155], v[64:65]
	v_pk_mul_f32 v[160:161], v[154:155], v[58:59]
	v_pk_mul_f32 v[162:163], v[154:155], v[60:61]
	v_exp_f32_e32 v156, v156
	v_exp_f32_e32 v157, v157
	v_exp_f32_e32 v158, v158
	v_exp_f32_e32 v159, v159
	v_exp_f32_e32 v160, v160
	v_exp_f32_e32 v161, v161
	v_exp_f32_e32 v162, v162
	v_exp_f32_e32 v163, v163
	v_pk_add_f32 v[156:157], v[156:157], 1.0 op_sel_hi:[1,0]
	v_pk_add_f32 v[158:159], v[158:159], 1.0 op_sel_hi:[1,0]
	v_pk_add_f32 v[160:161], v[160:161], 1.0 op_sel_hi:[1,0]
	v_pk_add_f32 v[162:163], v[162:163], 1.0 op_sel_hi:[1,0]
	v_rcp_f32_e32 v156, v156
	v_rcp_f32_e32 v157, v157
	v_rcp_f32_e32 v158, v158
	v_rcp_f32_e32 v159, v159
	v_rcp_f32_e32 v160, v160
	v_rcp_f32_e32 v161, v161
	v_rcp_f32_e32 v162, v162
	v_rcp_f32_e32 v163, v163
	v_pk_mul_f32 v[156:157], v[62:63], v[156:157]
	v_pk_mul_f32 v[158:159], v[64:65], v[158:159]
	v_pk_mul_f32 v[160:161], v[58:59], v[160:161]
	v_pk_mul_f32 v[162:163], v[60:61], v[162:163]
	v_pk_mul_f32 v[156:157], v[156:157], v[54:55]
	v_pk_mul_f32 v[158:159], v[158:159], v[56:57]
	v_pk_mul_f32 v[160:161], v[160:161], v[50:51]
	v_pk_mul_f32 v[162:163], v[162:163], v[52:53]
	v_cvt_pk_bf16_f32 v172, v156, v157
	v_cvt_pk_bf16_f32 v173, v158, v159
	v_cvt_pk_bf16_f32 v174, v160, v161
	v_cvt_pk_bf16_f32 v175, v162, v163
	global_store_dwordx4 v180, v[172:175], s[100:101]
	s_add_i32 s99, s99, -1
	s_cmp_eq_u32 s99, 0
	s_cbranch_scc1 .Lp2e_done
.Lp2e_rg5:
	s_add_u32 s100, s22, 0xc6000
	s_addc_u32 s101, s23, 0
	v_pk_mul_f32 v[164:165], v[154:155], v[46:47]
	v_pk_mul_f32 v[166:167], v[154:155], v[48:49]
	v_pk_mul_f32 v[168:169], v[154:155], v[42:43]
	v_pk_mul_f32 v[170:171], v[154:155], v[44:45]
	v_exp_f32_e32 v164, v164
	v_exp_f32_e32 v165, v165
	v_exp_f32_e32 v166, v166
	v_exp_f32_e32 v167, v167
	v_exp_f32_e32 v168, v168
	v_exp_f32_e32 v169, v169
	v_exp_f32_e32 v170, v170
	v_exp_f32_e32 v171, v171
	v_pk_add_f32 v[164:165], v[164:165], 1.0 op_sel_hi:[1,0]
	v_pk_add_f32 v[166:167], v[166:167], 1.0 op_sel_hi:[1,0]
	v_pk_add_f32 v[168:169], v[168:169], 1.0 op_sel_hi:[1,0]
	v_pk_add_f32 v[170:171], v[170:171], 1.0 op_sel_hi:[1,0]
	v_rcp_f32_e32 v164, v164
	v_rcp_f32_e32 v165, v165
	v_rcp_f32_e32 v166, v166
	v_rcp_f32_e32 v167, v167
	v_rcp_f32_e32 v168, v168
	v_rcp_f32_e32 v169, v169
	v_rcp_f32_e32 v170, v170
	v_rcp_f32_e32 v171, v171
	v_pk_mul_f32 v[164:165], v[46:47], v[164:165]
	v_pk_mul_f32 v[166:167], v[48:49], v[166:167]
	v_pk_mul_f32 v[168:169], v[42:43], v[168:169]
	v_pk_mul_f32 v[170:171], v[44:45], v[170:171]
	v_pk_mul_f32 v[164:165], v[164:165], v[38:39]
	v_pk_mul_f32 v[166:167], v[166:167], v[40:41]
	v_pk_mul_f32 v[168:169], v[168:169], v[34:35]
	v_pk_mul_f32 v[170:171], v[170:171], v[36:37]
	v_cvt_pk_bf16_f32 v176, v164, v165
	v_cvt_pk_bf16_f32 v177, v166, v167
	v_cvt_pk_bf16_f32 v178, v168, v169
	v_cvt_pk_bf16_f32 v179, v170, v171
	global_store_dwordx4 v180, v[176:179], s[100:101]
	s_add_i32 s99, s99, -1
	s_cmp_eq_u32 s99, 0
	s_cbranch_scc1 .Lp2e_done
; __device__ __forceinline__ u32x4 pack8(const f32x4 a, const f32x4 b) { u32x4 w; w.x = cvt_pk_bf16(a[0], a[1]); w.y = cvt_pk_bf16(a[2], a[3]); w.z = cvt_pk_bf16(b[0], b[1]); w.w = cvt_pk_bf16(b[2], b[3]); return w; }
; __device__ __forceinline__ float sigm(float v) { return __builtin_amdgcn_rcpf(1.f + __expf(-v)); }
; #define EPI_ROWS _Pragma("unroll") for (int ai = 0; ai < 2; ++ai) _Pragma("unroll") for (int m = 0; m < 4; ++m)
;     __device__ __forceinline__ void operator()(const f32x4 (&acc)[2][2][4][2], const Unit& u, int wr, int wc, int fr, int fq) const {
;     ...
;         EPI_ROWS { const int row = EPI_ROW;
;             f32x4 a0 = acc[ai][0][m][0], a1 = acc[ai][0][m][1], b0 = acc[ai][1][m][0], b1 = acc[ai][1][m][1];
;             if (NORM) { const float rs = rsv[ai][m]; a0 = a0 * rs + ba0; a1 = a1 * rs + ba1; b0 = b0 * rs + bb0; b1 = b1 * rs + bb1; }
;             f32x4 o0, o1;
; #pragma unroll
;             for (int i = 0; i < 4; ++i) { o0[i] = a0[i] * sigm(a0[i]) * b0[i]; o1[i] = a1[i] * sigm(a1[i]) * b1[i]; }
;             *(u32x4*)(act + (size_t)(row >> 1) * (2 * DFF) + (u.pn * 4 + wc) * 64 + (row & 1) * 32 + fq * 8) = pack8(o0, o1); }
.Lp2e_rg6:
	s_add_u32 s100, s22, 0xdc000
	s_addc_u32 s101, s23, 0
	v_pk_mul_f32 v[156:157], v[154:155], v[30:31]
	v_pk_mul_f32 v[158:159], v[154:155], v[32:33]
	v_pk_mul_f32 v[160:161], v[154:155], v[26:27]
	v_pk_mul_f32 v[162:163], v[154:155], v[28:29]
	v_exp_f32_e32 v156, v156
	v_exp_f32_e32 v157, v157
	v_exp_f32_e32 v158, v158
	v_exp_f32_e32 v159, v159
	v_exp_f32_e32 v160, v160
	v_exp_f32_e32 v161, v161
	v_exp_f32_e32 v162, v162
	v_exp_f32_e32 v163, v163
	v_pk_add_f32 v[156:157], v[156:157], 1.0 op_sel_hi:[1,0]
	v_pk_add_f32 v[158:159], v[158:159], 1.0 op_sel_hi:[1,0]
	v_pk_add_f32 v[160:161], v[160:161], 1.0 op_sel_hi:[1,0]
	v_pk_add_f32 v[162:163], v[162:163], 1.0 op_sel_hi:[1,0]
	v_rcp_f32_e32 v156, v156
	v_rcp_f32_e32 v157, v157
	v_rcp_f32_e32 v158, v158
	v_rcp_f32_e32 v159, v159
	v_rcp_f32_e32 v160, v160
	v_rcp_f32_e32 v161, v161
	v_rcp_f32_e32 v162, v162
	v_rcp_f32_e32 v163, v163
	v_pk_mul_f32 v[156:157], v[30:31], v[156:157]
	v_pk_mul_f32 v[158:159], v[32:33], v[158:159]
	v_pk_mul_f32 v[160:161], v[26:27], v[160:161]
	v_pk_mul_f32 v[162:163], v[28:29], v[162:163]
	v_pk_mul_f32 v[156:157], v[156:157], v[22:23]
	v_pk_mul_f32 v[158:159], v[158:159], v[24:25]
	v_pk_mul_f32 v[160:161], v[160:161], v[18:19]
	v_pk_mul_f32 v[162:163], v[162:163], v[20:21]
	v_cvt_pk_bf16_f32 v172, v156, v157
	v_cvt_pk_bf16_f32 v173, v158, v159
	v_cvt_pk_bf16_f32 v174, v160, v161
	v_cvt_pk_bf16_f32 v175, v162, v163
	global_store_dwordx4 v180, v[172:175], s[100:101]
	s_add_i32 s99, s99, -1
	s_cmp_eq_u32 s99, 0
	s_cbranch_scc1 .Lp2e_done
.Lp2e_rg7:
	s_add_u32 s100, s22, 0xf2000
	s_addc_u32 s101, s23, 0
	v_pk_mul_f32 v[164:165], v[154:155], v[14:15]
	v_pk_mul_f32 v[166:167], v[154:155], v[16:17]
	v_pk_mul_f32 v[168:169], v[154:155], v[10:11]
	v_pk_mul_f32 v[170:171], v[154:155], v[12:13]
	v_exp_f32_e32 v164, v164
	v_exp_f32_e32 v165, v165
	v_exp_f32_e32 v166, v166
	v_exp_f32_e32 v167, v167
	v_exp_f32_e32 v168, v168
	v_exp_f32_e32 v169, v169
	v_exp_f32_e32 v170, v170
	v_exp_f32_e32 v171, v171
	v_pk_add_f32 v[164:165], v[164:165], 1.0 op_sel_hi:[1,0]
	v_pk_add_f32 v[166:167], v[166:167], 1.0 op_sel_hi:[1,0]
	v_pk_add_f32 v[168:169], v[168:169], 1.0 op_sel_hi:[1,0]
	v_pk_add_f32 v[170:171], v[170:171], 1.0 op_sel_hi:[1,0]
	v_rcp_f32_e32 v164, v164
	v_rcp_f32_e32 v165, v165
	v_rcp_f32_e32 v166, v166
	v_rcp_f32_e32 v167, v167
	v_rcp_f32_e32 v168, v168
	v_rcp_f32_e32 v169, v169
	v_rcp_f32_e32 v170, v170
	v_rcp_f32_e32 v171, v171
	v_pk_mul_f32 v[164:165], v[14:15], v[164:165]
	v_pk_mul_f32 v[166:167], v[16:17], v[166:167]
	v_pk_mul_f32 v[168:169], v[10:11], v[168:169]
	v_pk_mul_f32 v[170:171], v[12:13], v[170:171]
	v_pk_mul_f32 v[164:165], v[164:165], v[6:7]
	v_pk_mul_f32 v[166:167], v[166:167], v[8:9]
	v_pk_mul_f32 v[168:169], v[168:169], v[2:3]
	v_pk_mul_f32 v[170:171], v[170:171], v[4:5]
	v_cvt_pk_bf16_f32 v176, v164, v165
	v_cvt_pk_bf16_f32 v177, v166, v167
	v_cvt_pk_bf16_f32 v178, v168, v169
	v_cvt_pk_bf16_f32 v179, v170, v171
	global_store_dwordx4 v180, v[176:179], s[100:101]
	s_add_i32 s99, s99, -1
	s_cmp_eq_u32 s99, 0
	s_cbranch_scc1 .Lp2e_done
	s_branch .Lp2e_rg0
.Lp2e_done:
	s_andn2_b64 vcc, exec, s[0:1]
	s_mov_b64 s[0:1], -1
	s_cbranch_vccnz .LBB0_204
	s_andn2_b64 vcc, exec, s[4:5]
	s_cbranch_vccnz .LBB0_203
	s_barrier
	s_branch .LBB0_203

; #define PG8_LAS __attribute__((address_space(3)))
; __device__ __forceinline__ u32x4 pack8(const f32x4 a, const f32x4 b) { u32x4 w; w.x = cvt_pk_bf16(a[0], a[1]); w.y = cvt_pk_bf16(a[2], a[3]); w.z = cvt_pk_bf16(b[0], b[1]); w.w = cvt_pk_bf16(b[2], b[3]); return w; }
; __device__ __forceinline__ float sigm(float v) { return __builtin_amdgcn_rcpf(1.f + __expf(-v)); }
; #define EPI_ROWS _Pragma("unroll") for (int ai = 0; ai < 2; ++ai) _Pragma("unroll") for (int m = 0; m < 4; ++m)
;     __device__ __forceinline__ void operator()(const f32x4 (&acc)[2][2][4][2], const Unit& u, int wr, int wc, int fr, int fq) const {
;         asm volatile("" : "+v"(fr), "+v"(fq));
;         const int b = u.pm >> 5, tcol = wc * 32 + fq * 8;
;         f32x4 ba0 = {0.f, 0.f, 0.f, 0.f}, ba1 = ba0, bb0 = ba0, bb1 = ba0;
;         if (NORM) { const PG8_LAS float* bp = (const PG8_LAS float*)(scr + 16384) + tcol; ba0 = *(const PG8_LAS f32x4*)bp; ba1 = *(const PG8_LAS f32x4*)(bp + 4); bb0 = *(const PG8_LAS f32x4*)(bp + HALF); bb1 = *(const PG8_LAS f32x4*)(bp + HALF + 4); }
;         float rsv[2][4];
;         if (NORM) { EPI_ROWS { rsv[ai][m] = rstd_lds(scr, EPI_LROW); asm volatile("" : "+v"(rsv[ai][m]) :: "memory"); } }
;         EPI_ROWS { const int row = EPI_ROW;
;             f32x4 a0 = acc[ai][0][m][0], a1 = acc[ai][0][m][1], b0 = acc[ai][1][m][0], b1 = acc[ai][1][m][1];
;             if (NORM) { const float rs = rsv[ai][m]; a0 = a0 * rs + ba0; a1 = a1 * rs + ba1; b0 = b0 * rs + bb0; b1 = b1 * rs + bb1; }
;             f32x4 o0, o1;
; #pragma unroll
;             for (int i = 0; i < 4; ++i) { o0[i] = a0[i] * sigm(a0[i]) * b0[i]; o1[i] = a1[i] * sigm(a1[i]) * b1[i]; }
;             *(u32x4*)(act + (size_t)(row >> 1) * (2 * DFF) + (u.pn * 4 + wc) * 64 + (row & 1) * 32 + fq * 8) = pack8(o0, o1); }
.LBB0_991:
	v_mov_b32_e32 v138, 0xbfb8aa3b
	v_mov_b32_e32 v139, 0xbfb8aa3b
	v_mov_b32_e32 v140, 0x358637bd
	v_lshlrev_b32_e32 v141, 6, v1
	v_lshl_add_u32 v168, v192, 5, s70
	ds_read_b128 v[200:203], v168
	ds_read_b128 v[204:207], v168 offset:16
	ds_read_b128 v[208:211], v168 offset:512
	ds_read_b128 v[212:215], v168 offset:528
	v_lshl_add_u32 v169, v192, 10, v141
	v_add_u32_e32 v169, s71, v169
	ds_read_b128 v[216:219], v169
	ds_read_b128 v[220:223], v169 offset:16
	ds_read_b128 v[224:227], v169 offset:32
	ds_read_b128 v[228:231], v169 offset:48
	ds_read_b128 v[160:163], v169 offset:8192
	ds_read_b128 v[164:167], v169 offset:8208
	ds_read_b128 v[98:101], v169 offset:8224
	ds_read_b128 v[106:109], v169 offset:8240
	s_waitcnt lgkmcnt(4)
	v_pk_add_f32 v[218:219], v[218:219], v[222:223]
	v_pk_add_f32 v[216:217], v[216:217], v[220:221]
	v_pk_add_f32 v[220:221], v[226:227], v[230:231]
	v_pk_add_f32 v[222:223], v[224:225], v[228:229]
	v_pk_add_f32 v[218:219], v[218:219], v[220:221]
	v_pk_add_f32 v[216:217], v[216:217], v[222:223]
	v_add_f32_e32 v216, v216, v217
	v_add_f32_e32 v218, v218, v219
	v_add_f32_e32 v216, v216, v218
	v_fmamk_f32 v216, v216, 0x3a800000, v140
	v_rsq_f32_e32 v216, v216
	s_waitcnt lgkmcnt(0)
	v_pk_add_f32 v[162:163], v[162:163], v[166:167]
	v_pk_add_f32 v[160:161], v[160:161], v[164:165]
	v_pk_add_f32 v[164:165], v[100:101], v[108:109]
	v_pk_add_f32 v[166:167], v[98:99], v[106:107]
	v_pk_add_f32 v[162:163], v[162:163], v[164:165]
	v_pk_add_f32 v[160:161], v[160:161], v[166:167]
	v_add_f32_e32 v160, v160, v161
	v_add_f32_e32 v162, v162, v163
	v_add_f32_e32 v160, v160, v162
	v_fmamk_f32 v160, v160, 0x3a800000, v140
	v_rsq_f32_e32 v160, v160
	v_lshlrev_b32_e32 v220, 2, v1
	v_add_u32_e32 v221, 0x40, v220
	v_add_u32_e32 v222, 0x80, v220
	v_add_u32_e32 v223, 0xc0, v220
	ds_bpermute_b32 v142, v220, v216
	ds_bpermute_b32 v144, v221, v216
	ds_bpermute_b32 v146, v222, v216
	ds_bpermute_b32 v148, v223, v216
	ds_bpermute_b32 v150, v220, v160
	ds_bpermute_b32 v152, v221, v160
	ds_bpermute_b32 v154, v222, v160
	ds_bpermute_b32 v156, v223, v160
	s_waitcnt lgkmcnt(0)
	v_lshrrev_b32_e32 v168, 1, v1
	v_mul_u32_u24_e32 v168, 0x2c00, v168
	v_and_b32_e32 v169, 1, v1
	v_lshl_add_u32 v168, v169, 6, v168
	v_lshl_add_u32 v168, v192, 4, v168
	s_lshl_b32 s21, s28, 8
	s_add_i32 s21, s21, s64
	s_lshr_b32 s21, s21, 1
	s_mul_i32 s21, s21, 0x2c00
	s_or_b32 s28, s34, s67
	s_lshl_b32 s28, s28, 1
	s_add_u32 s21, s21, s28
	s_add_u32 s28, s6, s21
	s_addc_u32 s29, s7, 0
	s_lshr_b32 s98, s64, 4
	s_lshr_b32 s99, s67, 6
	s_add_u32 s98, s98, s99
	s_mov_b32 s99, 8
	s_cmp_eq_u32 s98, 1
	s_cbranch_scc1 .Lp8e_rg1
	s_cmp_eq_u32 s98, 2
	s_cbranch_scc1 .Lp8e_rg2
	s_cmp_eq_u32 s98, 3
	s_cbranch_scc1 .Lp8e_rg3
	s_cmp_eq_u32 s98, 4
	s_cbranch_scc1 .Lp8e_rg4
	s_cmp_eq_u32 s98, 5
	s_cbranch_scc1 .Lp8e_rg5
	s_cmp_eq_u32 s98, 6
	s_cbranch_scc1 .Lp8e_rg6
	s_cmp_eq_u32 s98, 7
	s_cbranch_scc1 .Lp8e_rg7
.Lp8e_rg0:
	s_add_u32 s100, s28, 0x0
	s_addc_u32 s101, s29, 0
	v_pk_fma_f32 v[134:135], v[134:135], v[142:143], v[200:201] op_sel_hi:[1,0,1]
	v_pk_fma_f32 v[136:137], v[136:137], v[142:143], v[202:203] op_sel_hi:[1,0,1]
	v_pk_fma_f32 v[130:131], v[130:131], v[142:143], v[204:205] op_sel_hi:[1,0,1]
	v_pk_fma_f32 v[132:133], v[132:133], v[142:143], v[206:207] op_sel_hi:[1,0,1]
	v_pk_fma_f32 v[126:127], v[126:127], v[142:143], v[208:209] op_sel_hi:[1,0,1]
	v_pk_fma_f32 v[128:129], v[128:129], v[142:143], v[210:211] op_sel_hi:[1,0,1]
	v_pk_fma_f32 v[122:123], v[122:123], v[142:143], v[212:213] op_sel_hi:[1,0,1]
	v_pk_fma_f32 v[124:125], v[124:125], v[142:143], v[214:215] op_sel_hi:[1,0,1]
	v_pk_mul_f32 v[216:217], v[138:139], v[134:135]
	v_pk_mul_f32 v[218:219], v[138:139], v[136:137]
	v_pk_mul_f32 v[220:221], v[138:139], v[130:131]
	v_pk_mul_f32 v[222:223], v[138:139], v[132:133]
	v_exp_f32_e32 v216, v216
	v_exp_f32_e32 v217, v217
	v_exp_f32_e32 v218, v218
	v_exp_f32_e32 v219, v219
	v_exp_f32_e32 v220, v220
	v_exp_f32_e32 v221, v221
	v_exp_f32_e32 v222, v222
	v_exp_f32_e32 v223, v223
	v_pk_add_f32 v[216:217], v[216:217], 1.0 op_sel_hi:[1,0]
	v_pk_add_f32 v[218:219], v[218:219], 1.0 op_sel_hi:[1,0]
	v_pk_add_f32 v[220:221], v[220:221], 1.0 op_sel_hi:[1,0]
	v_pk_add_f32 v[222:223], v[222:223], 1.0 op_sel_hi:[1,0]
	v_rcp_f32_e32 v216, v216
	v_rcp_f32_e32 v217, v217
	v_rcp_f32_e32 v218, v218
	v_rcp_f32_e32 v219, v219
	v_rcp_f32_e32 v220, v220
	v_rcp_f32_e32 v221, v221
	v_rcp_f32_e32 v222, v222
	v_rcp_f32_e32 v223, v223
	v_pk_mul_f32 v[216:217], v[134:135], v[216:217]
	v_pk_mul_f32 v[218:219], v[136:137], v[218:219]
	v_pk_mul_f32 v[220:221], v[130:131], v[220:221]
	v_pk_mul_f32 v[222:223], v[132:133], v[222:223]
	v_pk_mul_f32 v[216:217], v[216:217], v[126:127]
	v_pk_mul_f32 v[218:219], v[218:219], v[128:129]
	v_pk_mul_f32 v[220:221], v[220:221], v[122:123]
	v_pk_mul_f32 v[222:223], v[222:223], v[124:125]
	v_cvt_pk_bf16_f32 v160, v216, v217
	v_cvt_pk_bf16_f32 v161, v218, v219
	v_cvt_pk_bf16_f32 v162, v220, v221
	v_cvt_pk_bf16_f32 v163, v222, v223
	global_store_dwordx4 v168, v[160:163], s[100:101]
	s_add_i32 s99, s99, -1
	s_cmp_eq_u32 s99, 0
	s_cbranch_scc1 .Lp8e_done
; __device__ __forceinline__ u32x4 pack8(const f32x4 a, const f32x4 b) { u32x4 w; w.x = cvt_pk_bf16(a[0], a[1]); w.y = cvt_pk_bf16(a[2], a[3]); w.z = cvt_pk_bf16(b[0], b[1]); w.w = cvt_pk_bf16(b[2], b[3]); return w; }
; __device__ __forceinline__ float sigm(float v) { return __builtin_amdgcn_rcpf(1.f + __expf(-v)); }
; #define EPI_ROWS _Pragma("unroll") for (int ai = 0; ai < 2; ++ai) _Pragma("unroll") for (int m = 0; m < 4; ++m)
;     __device__ __forceinline__ void operator()(const f32x4 (&acc)[2][2][4][2], const Unit& u, int wr, int wc, int fr, int fq) const {
;     ...
;         EPI_ROWS { const int row = EPI_ROW;
;             f32x4 a0 = acc[ai][0][m][0], a1 = acc[ai][0][m][1], b0 = acc[ai][1][m][0], b1 = acc[ai][1][m][1];
;             if (NORM) { const float rs = rsv[ai][m]; a0 = a0 * rs + ba0; a1 = a1 * rs + ba1; b0 = b0 * rs + bb0; b1 = b1 * rs + bb1; }
;             f32x4 o0, o1;
; #pragma unroll
;             for (int i = 0; i < 4; ++i) { o0[i] = a0[i] * sigm(a0[i]) * b0[i]; o1[i] = a1[i] * sigm(a1[i]) * b1[i]; }
;             *(u32x4*)(act + (size_t)(row >> 1) * (2 * DFF) + (u.pn * 4 + wc) * 64 + (row & 1) * 32 + fq * 8) = pack8(o0, o1); }
.Lp8e_rg1:
	s_add_u32 s100, s28, 0x16000
	s_addc_u32 s101, s29, 0
	v_pk_fma_f32 v[118:119], v[118:119], v[144:145], v[200:201] op_sel_hi:[1,0,1]
	v_pk_fma_f32 v[120:121], v[120:121], v[144:145], v[202:203] op_sel_hi:[1,0,1]
	v_pk_fma_f32 v[114:115], v[114:115], v[144:145], v[204:205] op_sel_hi:[1,0,1]
	v_pk_fma_f32 v[116:117], v[116:117], v[144:145], v[206:207] op_sel_hi:[1,0,1]
	v_pk_fma_f32 v[110:111], v[110:111], v[144:145], v[208:209] op_sel_hi:[1,0,1]
	v_pk_fma_f32 v[112:113], v[112:113], v[144:145], v[210:211] op_sel_hi:[1,0,1]
	v_pk_fma_f32 v[102:103], v[102:103], v[144:145], v[212:213] op_sel_hi:[1,0,1]
	v_pk_fma_f32 v[104:105], v[104:105], v[144:145], v[214:215] op_sel_hi:[1,0,1]
	v_pk_mul_f32 v[224:225], v[138:139], v[118:119]
	v_pk_mul_f32 v[226:227], v[138:139], v[120:121]
	v_pk_mul_f32 v[228:229], v[138:139], v[114:115]
	v_pk_mul_f32 v[230:231], v[138:139], v[116:117]
	v_exp_f32_e32 v224, v224
	v_exp_f32_e32 v225, v225
	v_exp_f32_e32 v226, v226
	v_exp_f32_e32 v227, v227
	v_exp_f32_e32 v228, v228
	v_exp_f32_e32 v229, v229
	v_exp_f32_e32 v230, v230
	v_exp_f32_e32 v231, v231
	v_pk_add_f32 v[224:225], v[224:225], 1.0 op_sel_hi:[1,0]
	v_pk_add_f32 v[226:227], v[226:227], 1.0 op_sel_hi:[1,0]
	v_pk_add_f32 v[228:229], v[228:229], 1.0 op_sel_hi:[1,0]
	v_pk_add_f32 v[230:231], v[230:231], 1.0 op_sel_hi:[1,0]
	v_rcp_f32_e32 v224, v224
	v_rcp_f32_e32 v225, v225
	v_rcp_f32_e32 v226, v226
	v_rcp_f32_e32 v227, v227
	v_rcp_f32_e32 v228, v228
	v_rcp_f32_e32 v229, v229
	v_rcp_f32_e32 v230, v230
	v_rcp_f32_e32 v231, v231
	v_pk_mul_f32 v[224:225], v[118:119], v[224:225]
	v_pk_mul_f32 v[226:227], v[120:121], v[226:227]
	v_pk_mul_f32 v[228:229], v[114:115], v[228:229]
	v_pk_mul_f32 v[230:231], v[116:117], v[230:231]
	v_pk_mul_f32 v[224:225], v[224:225], v[110:111]
	v_pk_mul_f32 v[226:227], v[226:227], v[112:113]
	v_pk_mul_f32 v[228:229], v[228:229], v[102:103]
	v_pk_mul_f32 v[230:231], v[230:231], v[104:105]
	v_cvt_pk_bf16_f32 v164, v224, v225
	v_cvt_pk_bf16_f32 v165, v226, v227
	v_cvt_pk_bf16_f32 v166, v228, v229
	v_cvt_pk_bf16_f32 v167, v230, v231
	global_store_dwordx4 v168, v[164:167], s[100:101]
	s_add_i32 s99, s99, -1
	s_cmp_eq_u32 s99, 0
	s_cbranch_scc1 .Lp8e_done
.Lp8e_rg2:
	s_add_u32 s100, s28, 0x2c000
	s_addc_u32 s101, s29, 0
	v_pk_fma_f32 v[94:95], v[94:95], v[146:147], v[200:201] op_sel_hi:[1,0,1]
	v_pk_fma_f32 v[96:97], v[96:97], v[146:147], v[202:203] op_sel_hi:[1,0,1]
	v_pk_fma_f32 v[90:91], v[90:91], v[146:147], v[204:205] op_sel_hi:[1,0,1]
	v_pk_fma_f32 v[92:93], v[92:93], v[146:147], v[206:207] op_sel_hi:[1,0,1]
	v_pk_fma_f32 v[86:87], v[86:87], v[146:147], v[208:209] op_sel_hi:[1,0,1]
	v_pk_fma_f32 v[88:89], v[88:89], v[146:147], v[210:211] op_sel_hi:[1,0,1]
	v_pk_fma_f32 v[82:83], v[82:83], v[146:147], v[212:213] op_sel_hi:[1,0,1]
	v_pk_fma_f32 v[84:85], v[84:85], v[146:147], v[214:215] op_sel_hi:[1,0,1]
	v_pk_mul_f32 v[216:217], v[138:139], v[94:95]
	v_pk_mul_f32 v[218:219], v[138:139], v[96:97]
	v_pk_mul_f32 v[220:221], v[138:139], v[90:91]
	v_pk_mul_f32 v[222:223], v[138:139], v[92:93]
	v_exp_f32_e32 v216, v216
	v_exp_f32_e32 v217, v217
	v_exp_f32_e32 v218, v218
	v_exp_f32_e32 v219, v219
	v_exp_f32_e32 v220, v220
	v_exp_f32_e32 v221, v221
	v_exp_f32_e32 v222, v222
	v_exp_f32_e32 v223, v223
	v_pk_add_f32 v[216:217], v[216:217], 1.0 op_sel_hi:[1,0]
	v_pk_add_f32 v[218:219], v[218:219], 1.0 op_sel_hi:[1,0]
	v_pk_add_f32 v[220:221], v[220:221], 1.0 op_sel_hi:[1,0]
	v_pk_add_f32 v[222:223], v[222:223], 1.0 op_sel_hi:[1,0]
	v_rcp_f32_e32 v216, v216
	v_rcp_f32_e32 v217, v217
	v_rcp_f32_e32 v218, v218
	v_rcp_f32_e32 v219, v219
	v_rcp_f32_e32 v220, v220
	v_rcp_f32_e32 v221, v221
	v_rcp_f32_e32 v222, v222
	v_rcp_f32_e32 v223, v223
	v_pk_mul_f32 v[216:217], v[94:95], v[216:217]
	v_pk_mul_f32 v[218:219], v[96:97], v[218:219]
	v_pk_mul_f32 v[220:221], v[90:91], v[220:221]
	v_pk_mul_f32 v[222:223], v[92:93], v[222:223]
	v_pk_mul_f32 v[216:217], v[216:217], v[86:87]
	v_pk_mul_f32 v[218:219], v[218:219], v[88:89]
	v_pk_mul_f32 v[220:221], v[220:221], v[82:83]
	v_pk_mul_f32 v[222:223], v[222:223], v[84:85]
	v_cvt_pk_bf16_f32 v160, v216, v217
	v_cvt_pk_bf16_f32 v161, v218, v219
	v_cvt_pk_bf16_f32 v162, v220, v221
	v_cvt_pk_bf16_f32 v163, v222, v223
	global_store_dwordx4 v168, v[160:163], s[100:101]
	s_add_i32 s99, s99, -1
	s_cmp_eq_u32 s99, 0
	s_cbranch_scc1 .Lp8e_done
.Lp8e_rg3:
	s_add_u32 s100, s28, 0x42000
	s_addc_u32 s101, s29, 0
	v_pk_fma_f32 v[78:79], v[78:79], v[148:149], v[200:201] op_sel_hi:[1,0,1]
	v_pk_fma_f32 v[80:81], v[80:81], v[148:149], v[202:203] op_sel_hi:[1,0,1]
	v_pk_fma_f32 v[74:75], v[74:75], v[148:149], v[204:205] op_sel_hi:[1,0,1]
	v_pk_fma_f32 v[76:77], v[76:77], v[148:149], v[206:207] op_sel_hi:[1,0,1]
	v_pk_fma_f32 v[70:71], v[70:71], v[148:149], v[208:209] op_sel_hi:[1,0,1]
	v_pk_fma_f32 v[72:73], v[72:73], v[148:149], v[210:211] op_sel_hi:[1,0,1]
	v_pk_fma_f32 v[66:67], v[66:67], v[148:149], v[212:213] op_sel_hi:[1,0,1]
	v_pk_fma_f32 v[68:69], v[68:69], v[148:149], v[214:215] op_sel_hi:[1,0,1]
	v_pk_mul_f32 v[224:225], v[138:139], v[78:79]
	v_pk_mul_f32 v[226:227], v[138:139], v[80:81]
	v_pk_mul_f32 v[228:229], v[138:139], v[74:75]
	v_pk_mul_f32 v[230:231], v[138:139], v[76:77]
	v_exp_f32_e32 v224, v224
	v_exp_f32_e32 v225, v225
	v_exp_f32_e32 v226, v226
	v_exp_f32_e32 v227, v227
	v_exp_f32_e32 v228, v228
	v_exp_f32_e32 v229, v229
	v_exp_f32_e32 v230, v230
	v_exp_f32_e32 v231, v231
	v_pk_add_f32 v[224:225], v[224:225], 1.0 op_sel_hi:[1,0]
	v_pk_add_f32 v[226:227], v[226:227], 1.0 op_sel_hi:[1,0]
	v_pk_add_f32 v[228:229], v[228:229], 1.0 op_sel_hi:[1,0]
	v_pk_add_f32 v[230:231], v[230:231], 1.0 op_sel_hi:[1,0]
	v_rcp_f32_e32 v224, v224
	v_rcp_f32_e32 v225, v225
	v_rcp_f32_e32 v226, v226
	v_rcp_f32_e32 v227, v227
	v_rcp_f32_e32 v228, v228
	v_rcp_f32_e32 v229, v229
	v_rcp_f32_e32 v230, v230
	v_rcp_f32_e32 v231, v231
	v_pk_mul_f32 v[224:225], v[78:79], v[224:225]
	v_pk_mul_f32 v[226:227], v[80:81], v[226:227]
	v_pk_mul_f32 v[228:229], v[74:75], v[228:229]
	v_pk_mul_f32 v[230:231], v[76:77], v[230:231]
	v_pk_mul_f32 v[224:225], v[224:225], v[70:71]
	v_pk_mul_f32 v[226:227], v[226:227], v[72:73]
	v_pk_mul_f32 v[228:229], v[228:229], v[66:67]
	v_pk_mul_f32 v[230:231], v[230:231], v[68:69]
	v_cvt_pk_bf16_f32 v164, v224, v225
	v_cvt_pk_bf16_f32 v165, v226, v227
	v_cvt_pk_bf16_f32 v166, v228, v229
	v_cvt_pk_bf16_f32 v167, v230, v231
	global_store_dwordx4 v168, v[164:167], s[100:101]
	s_add_i32 s99, s99, -1
	s_cmp_eq_u32 s99, 0
	s_cbranch_scc1 .Lp8e_done
; __device__ __forceinline__ u32x4 pack8(const f32x4 a, const f32x4 b) { u32x4 w; w.x = cvt_pk_bf16(a[0], a[1]); w.y = cvt_pk_bf16(a[2], a[3]); w.z = cvt_pk_bf16(b[0], b[1]); w.w = cvt_pk_bf16(b[2], b[3]); return w; }
; __device__ __forceinline__ float sigm(float v) { return __builtin_amdgcn_rcpf(1.f + __expf(-v)); }
; #define EPI_ROWS _Pragma("unroll") for (int ai = 0; ai < 2; ++ai) _Pragma("unroll") for (int m = 0; m < 4; ++m)
;     __device__ __forceinline__ void operator()(const f32x4 (&acc)[2][2][4][2], const Unit& u, int wr, int wc, int fr, int fq) const {
;     ...
;         EPI_ROWS { const int row = EPI_ROW;
;             f32x4 a0 = acc[ai][0][m][0], a1 = acc[ai][0][m][1], b0 = acc[ai][1][m][0], b1 = acc[ai][1][m][1];
;             if (NORM) { const float rs = rsv[ai][m]; a0 = a0 * rs + ba0; a1 = a1 * rs + ba1; b0 = b0 * rs + bb0; b1 = b1 * rs + bb1; }
;             f32x4 o0, o1;
; #pragma unroll
;             for (int i = 0; i < 4; ++i) { o0[i] = a0[i] * sigm(a0[i]) * b0[i]; o1[i] = a1[i] * sigm(a1[i]) * b1[i]; }
;             *(u32x4*)(act + (size_t)(row >> 1) * (2 * DFF) + (u.pn * 4 + wc) * 64 + (row & 1) * 32 + fq * 8) = pack8(o0, o1); }
.Lp8e_rg4:
	s_add_u32 s100, s28, 0xb0000
	s_addc_u32 s101, s29, 0
	v_pk_fma_f32 v[62:63], v[62:63], v[150:151], v[200:201] op_sel_hi:[1,0,1]
	v_pk_fma_f32 v[64:65], v[64:65], v[150:151], v[202:203] op_sel_hi:[1,0,1]
	v_pk_fma_f32 v[58:59], v[58:59], v[150:151], v[204:205] op_sel_hi:[1,0,1]
	v_pk_fma_f32 v[60:61], v[60:61], v[150:151], v[206:207] op_sel_hi:[1,0,1]
	v_pk_fma_f32 v[54:55], v[54:55], v[150:151], v[208:209] op_sel_hi:[1,0,1]
	v_pk_fma_f32 v[56:57], v[56:57], v[150:151], v[210:211] op_sel_hi:[1,0,1]
	v_pk_fma_f32 v[50:51], v[50:51], v[150:151], v[212:213] op_sel_hi:[1,0,1]
	v_pk_fma_f32 v[52:53], v[52:53], v[150:151], v[214:215] op_sel_hi:[1,0,1]
	v_pk_mul_f32 v[216:217], v[138:139], v[62:63]
	v_pk_mul_f32 v[218:219], v[138:139], v[64:65]
	v_pk_mul_f32 v[220:221], v[138:139], v[58:59]
	v_pk_mul_f32 v[222:223], v[138:139], v[60:61]
	v_exp_f32_e32 v216, v216
	v_exp_f32_e32 v217, v217
	v_exp_f32_e32 v218, v218
	v_exp_f32_e32 v219, v219
	v_exp_f32_e32 v220, v220
	v_exp_f32_e32 v221, v221
	v_exp_f32_e32 v222, v222
	v_exp_f32_e32 v223, v223
	v_pk_add_f32 v[216:217], v[216:217], 1.0 op_sel_hi:[1,0]
	v_pk_add_f32 v[218:219], v[218:219], 1.0 op_sel_hi:[1,0]
	v_pk_add_f32 v[220:221], v[220:221], 1.0 op_sel_hi:[1,0]
	v_pk_add_f32 v[222:223], v[222:223], 1.0 op_sel_hi:[1,0]
	v_rcp_f32_e32 v216, v216
	v_rcp_f32_e32 v217, v217
	v_rcp_f32_e32 v218, v218
	v_rcp_f32_e32 v219, v219
	v_rcp_f32_e32 v220, v220
	v_rcp_f32_e32 v221, v221
	v_rcp_f32_e32 v222, v222
	v_rcp_f32_e32 v223, v223
	v_pk_mul_f32 v[216:217], v[62:63], v[216:217]
	v_pk_mul_f32 v[218:219], v[64:65], v[218:219]
	v_pk_mul_f32 v[220:221], v[58:59], v[220:221]
	v_pk_mul_f32 v[222:223], v[60:61], v[222:223]
	v_pk_mul_f32 v[216:217], v[216:217], v[54:55]
	v_pk_mul_f32 v[218:219], v[218:219], v[56:57]
	v_pk_mul_f32 v[220:221], v[220:221], v[50:51]
	v_pk_mul_f32 v[222:223], v[222:223], v[52:53]
	v_cvt_pk_bf16_f32 v160, v216, v217
	v_cvt_pk_bf16_f32 v161, v218, v219
	v_cvt_pk_bf16_f32 v162, v220, v221
	v_cvt_pk_bf16_f32 v163, v222, v223
	global_store_dwordx4 v168, v[160:163], s[100:101]
	s_add_i32 s99, s99, -1
	s_cmp_eq_u32 s99, 0
	s_cbranch_scc1 .Lp8e_done
.Lp8e_rg5:
	s_add_u32 s100, s28, 0xc6000
	s_addc_u32 s101, s29, 0
	v_pk_fma_f32 v[46:47], v[46:47], v[152:153], v[200:201] op_sel_hi:[1,0,1]
	v_pk_fma_f32 v[48:49], v[48:49], v[152:153], v[202:203] op_sel_hi:[1,0,1]
	v_pk_fma_f32 v[42:43], v[42:43], v[152:153], v[204:205] op_sel_hi:[1,0,1]
	v_pk_fma_f32 v[44:45], v[44:45], v[152:153], v[206:207] op_sel_hi:[1,0,1]
	v_pk_fma_f32 v[38:39], v[38:39], v[152:153], v[208:209] op_sel_hi:[1,0,1]
	v_pk_fma_f32 v[40:41], v[40:41], v[152:153], v[210:211] op_sel_hi:[1,0,1]
	v_pk_fma_f32 v[34:35], v[34:35], v[152:153], v[212:213] op_sel_hi:[1,0,1]
	v_pk_fma_f32 v[36:37], v[36:37], v[152:153], v[214:215] op_sel_hi:[1,0,1]
	v_pk_mul_f32 v[224:225], v[138:139], v[46:47]
	v_pk_mul_f32 v[226:227], v[138:139], v[48:49]
	v_pk_mul_f32 v[228:229], v[138:139], v[42:43]
	v_pk_mul_f32 v[230:231], v[138:139], v[44:45]
	v_exp_f32_e32 v224, v224
	v_exp_f32_e32 v225, v225
	v_exp_f32_e32 v226, v226
	v_exp_f32_e32 v227, v227
	v_exp_f32_e32 v228, v228
	v_exp_f32_e32 v229, v229
	v_exp_f32_e32 v230, v230
	v_exp_f32_e32 v231, v231
	v_pk_add_f32 v[224:225], v[224:225], 1.0 op_sel_hi:[1,0]
	v_pk_add_f32 v[226:227], v[226:227], 1.0 op_sel_hi:[1,0]
	v_pk_add_f32 v[228:229], v[228:229], 1.0 op_sel_hi:[1,0]
	v_pk_add_f32 v[230:231], v[230:231], 1.0 op_sel_hi:[1,0]
	v_rcp_f32_e32 v224, v224
	v_rcp_f32_e32 v225, v225
	v_rcp_f32_e32 v226, v226
	v_rcp_f32_e32 v227, v227
	v_rcp_f32_e32 v228, v228
	v_rcp_f32_e32 v229, v229
	v_rcp_f32_e32 v230, v230
	v_rcp_f32_e32 v231, v231
	v_pk_mul_f32 v[224:225], v[46:47], v[224:225]
	v_pk_mul_f32 v[226:227], v[48:49], v[226:227]
	v_pk_mul_f32 v[228:229], v[42:43], v[228:229]
	v_pk_mul_f32 v[230:231], v[44:45], v[230:231]
	v_pk_mul_f32 v[224:225], v[224:225], v[38:39]
	v_pk_mul_f32 v[226:227], v[226:227], v[40:41]
	v_pk_mul_f32 v[228:229], v[228:229], v[34:35]
	v_pk_mul_f32 v[230:231], v[230:231], v[36:37]
	v_cvt_pk_bf16_f32 v164, v224, v225
	v_cvt_pk_bf16_f32 v165, v226, v227
	v_cvt_pk_bf16_f32 v166, v228, v229
	v_cvt_pk_bf16_f32 v167, v230, v231
	global_store_dwordx4 v168, v[164:167], s[100:101]
	s_add_i32 s99, s99, -1
	s_cmp_eq_u32 s99, 0
	s_cbranch_scc1 .Lp8e_done
; __device__ __forceinline__ u32x4 pack8(const f32x4 a, const f32x4 b) { u32x4 w; w.x = cvt_pk_bf16(a[0], a[1]); w.y = cvt_pk_bf16(a[2], a[3]); w.z = cvt_pk_bf16(b[0], b[1]); w.w = cvt_pk_bf16(b[2], b[3]); return w; }
; __device__ __forceinline__ float sigm(float v) { return __builtin_amdgcn_rcpf(1.f + __expf(-v)); }
; #define EPI_ROWS _Pragma("unroll") for (int ai = 0; ai < 2; ++ai) _Pragma("unroll") for (int m = 0; m < 4; ++m)
;     __device__ __forceinline__ void operator()(const f32x4 (&acc)[2][2][4][2], const Unit& u, int wr, int wc, int fr, int fq) const {
;     ...
;         EPI_ROWS { const int row = EPI_ROW;
;             f32x4 a0 = acc[ai][0][m][0], a1 = acc[ai][0][m][1], b0 = acc[ai][1][m][0], b1 = acc[ai][1][m][1];
;             if (NORM) { const float rs = rsv[ai][m]; a0 = a0 * rs + ba0; a1 = a1 * rs + ba1; b0 = b0 * rs + bb0; b1 = b1 * rs + bb1; }
;             f32x4 o0, o1;
; #pragma unroll
;             for (int i = 0; i < 4; ++i) { o0[i] = a0[i] * sigm(a0[i]) * b0[i]; o1[i] = a1[i] * sigm(a1[i]) * b1[i]; }
;             *(u32x4*)(act + (size_t)(row >> 1) * (2 * DFF) + (u.pn * 4 + wc) * 64 + (row & 1) * 32 + fq * 8) = pack8(o0, o1); }
.Lp8e_rg6:
	s_add_u32 s100, s28, 0xdc000
	s_addc_u32 s101, s29, 0
	v_pk_fma_f32 v[30:31], v[30:31], v[154:155], v[200:201] op_sel_hi:[1,0,1]
	v_pk_fma_f32 v[32:33], v[32:33], v[154:155], v[202:203] op_sel_hi:[1,0,1]
	v_pk_fma_f32 v[26:27], v[26:27], v[154:155], v[204:205] op_sel_hi:[1,0,1]
	v_pk_fma_f32 v[28:29], v[28:29], v[154:155], v[206:207] op_sel_hi:[1,0,1]
	v_pk_fma_f32 v[22:23], v[22:23], v[154:155], v[208:209] op_sel_hi:[1,0,1]
	v_pk_fma_f32 v[24:25], v[24:25], v[154:155], v[210:211] op_sel_hi:[1,0,1]
	v_pk_fma_f32 v[18:19], v[18:19], v[154:155], v[212:213] op_sel_hi:[1,0,1]
	v_pk_fma_f32 v[20:21], v[20:21], v[154:155], v[214:215] op_sel_hi:[1,0,1]
	v_pk_mul_f32 v[216:217], v[138:139], v[30:31]
	v_pk_mul_f32 v[218:219], v[138:139], v[32:33]
	v_pk_mul_f32 v[220:221], v[138:139], v[26:27]
	v_pk_mul_f32 v[222:223], v[138:139], v[28:29]
	v_exp_f32_e32 v216, v216
	v_exp_f32_e32 v217, v217
	v_exp_f32_e32 v218, v218
	v_exp_f32_e32 v219, v219
	v_exp_f32_e32 v220, v220
	v_exp_f32_e32 v221, v221
	v_exp_f32_e32 v222, v222
	v_exp_f32_e32 v223, v223
	v_pk_add_f32 v[216:217], v[216:217], 1.0 op_sel_hi:[1,0]
	v_pk_add_f32 v[218:219], v[218:219], 1.0 op_sel_hi:[1,0]
	v_pk_add_f32 v[220:221], v[220:221], 1.0 op_sel_hi:[1,0]
	v_pk_add_f32 v[222:223], v[222:223], 1.0 op_sel_hi:[1,0]
	v_rcp_f32_e32 v216, v216
	v_rcp_f32_e32 v217, v217
	v_rcp_f32_e32 v218, v218
	v_rcp_f32_e32 v219, v219
	v_rcp_f32_e32 v220, v220
	v_rcp_f32_e32 v221, v221
	v_rcp_f32_e32 v222, v222
	v_rcp_f32_e32 v223, v223
	v_pk_mul_f32 v[216:217], v[30:31], v[216:217]
	v_pk_mul_f32 v[218:219], v[32:33], v[218:219]
	v_pk_mul_f32 v[220:221], v[26:27], v[220:221]
	v_pk_mul_f32 v[222:223], v[28:29], v[222:223]
	v_pk_mul_f32 v[216:217], v[216:217], v[22:23]
	v_pk_mul_f32 v[218:219], v[218:219], v[24:25]
	v_pk_mul_f32 v[220:221], v[220:221], v[18:19]
	v_pk_mul_f32 v[222:223], v[222:223], v[20:21]
	v_cvt_pk_bf16_f32 v160, v216, v217
	v_cvt_pk_bf16_f32 v161, v218, v219
	v_cvt_pk_bf16_f32 v162, v220, v221
	v_cvt_pk_bf16_f32 v163, v222, v223
	global_store_dwordx4 v168, v[160:163], s[100:101]
	s_add_i32 s99, s99, -1
	s_cmp_eq_u32 s99, 0
	s_cbranch_scc1 .Lp8e_done
.Lp8e_rg7:
	s_add_u32 s100, s28, 0xf2000
	s_addc_u32 s101, s29, 0
	v_pk_fma_f32 v[14:15], v[14:15], v[156:157], v[200:201] op_sel_hi:[1,0,1]
	v_pk_fma_f32 v[16:17], v[16:17], v[156:157], v[202:203] op_sel_hi:[1,0,1]
	v_pk_fma_f32 v[10:11], v[10:11], v[156:157], v[204:205] op_sel_hi:[1,0,1]
	v_pk_fma_f32 v[12:13], v[12:13], v[156:157], v[206:207] op_sel_hi:[1,0,1]
	v_pk_fma_f32 v[6:7], v[6:7], v[156:157], v[208:209] op_sel_hi:[1,0,1]
	v_pk_fma_f32 v[8:9], v[8:9], v[156:157], v[210:211] op_sel_hi:[1,0,1]
	v_pk_fma_f32 v[2:3], v[2:3], v[156:157], v[212:213] op_sel_hi:[1,0,1]
	v_pk_fma_f32 v[4:5], v[4:5], v[156:157], v[214:215] op_sel_hi:[1,0,1]
	v_pk_mul_f32 v[224:225], v[138:139], v[14:15]
	v_pk_mul_f32 v[226:227], v[138:139], v[16:17]
	v_pk_mul_f32 v[228:229], v[138:139], v[10:11]
	v_pk_mul_f32 v[230:231], v[138:139], v[12:13]
	v_exp_f32_e32 v224, v224
	v_exp_f32_e32 v225, v225
	v_exp_f32_e32 v226, v226
	v_exp_f32_e32 v227, v227
	v_exp_f32_e32 v228, v228
	v_exp_f32_e32 v229, v229
	v_exp_f32_e32 v230, v230
	v_exp_f32_e32 v231, v231
	v_pk_add_f32 v[224:225], v[224:225], 1.0 op_sel_hi:[1,0]
	v_pk_add_f32 v[226:227], v[226:227], 1.0 op_sel_hi:[1,0]
	v_pk_add_f32 v[228:229], v[228:229], 1.0 op_sel_hi:[1,0]
	v_pk_add_f32 v[230:231], v[230:231], 1.0 op_sel_hi:[1,0]
	v_rcp_f32_e32 v224, v224
	v_rcp_f32_e32 v225, v225
	v_rcp_f32_e32 v226, v226
	v_rcp_f32_e32 v227, v227
	v_rcp_f32_e32 v228, v228
	v_rcp_f32_e32 v229, v229
	v_rcp_f32_e32 v230, v230
	v_rcp_f32_e32 v231, v231
	v_pk_mul_f32 v[224:225], v[14:15], v[224:225]
	v_pk_mul_f32 v[226:227], v[16:17], v[226:227]
	v_pk_mul_f32 v[228:229], v[10:11], v[228:229]
	v_pk_mul_f32 v[230:231], v[12:13], v[230:231]
	v_pk_mul_f32 v[224:225], v[224:225], v[6:7]
	v_pk_mul_f32 v[226:227], v[226:227], v[8:9]
	v_pk_mul_f32 v[228:229], v[228:229], v[2:3]
	v_pk_mul_f32 v[230:231], v[230:231], v[4:5]
	v_cvt_pk_bf16_f32 v164, v224, v225
	v_cvt_pk_bf16_f32 v165, v226, v227
	v_cvt_pk_bf16_f32 v166, v228, v229
	v_cvt_pk_bf16_f32 v167, v230, v231
	global_store_dwordx4 v168, v[164:167], s[100:101]
	s_add_i32 s99, s99, -1
	s_cmp_eq_u32 s99, 0
	s_cbranch_scc1 .Lp8e_done
	s_branch .Lp8e_rg0
.Lp8e_done:
	s_andn2_b64 vcc, exec, s[2:3]
	s_mov_b64 s[2:3], -1
	s_cbranch_vccnz .LBB0_981
	s_andn2_b64 vcc, exec, s[4:5]
	s_cbranch_vccnz .LBB0_980
	s_barrier
	s_branch .LBB0_980
